# E4 + async early buffer_wbl2 by every 8th local arriver at each grid barrier (takes L2 write-back off the leader's critical path)
# speedup vs baseline: 1.0028x; 1.0028x over previous
; __device__ __forceinline__ unsigned xb_ld(unsigned* p)              { return __hip_atomic_load(p, __ATOMIC_RELAXED, __HIP_MEMORY_SCOPE_AGENT); }
; __device__ __forceinline__ unsigned xb_add(unsigned* p, unsigned v) { return __hip_atomic_fetch_add(p, v, __ATOMIC_RELAXED, __HIP_MEMORY_SCOPE_AGENT); }
; #define XB_SPIN(cond, bar) do { unsigned _sp = 0; while (cond) { __builtin_amdgcn_s_sleep(1); \
;     if ((++_sp & 255u) == 0u) { if (xb_ld(&(bar)[XB_TMO])) break; if (_sp > XB_SPIN_CAP) { atomicAdd(&(bar)[XB_TMO], 1u); break; } } } } while (0)
; __device__ __forceinline__ void xcd_barrier(const XcdBarrier& b) {
;     ...
;     if (threadIdx.x == 0) {
;         unsigned* bar = b.bar;
;         __builtin_amdgcn_s_waitcnt(0);
;         unsigned nloc = b.st[0], nx = b.st[1];
;         if (nloc == 0u) { xcd_barrier_complete(bar, b.x, nloc, nx); b.st[0] = nloc; b.st[1] = nx; }
;         const unsigned old = xb_add(&bar[XB_XSUB(b.x)], 1u);
;         const unsigned gen = old / nloc;
;         if (old + 1u == (gen + 1u) * nloc) {
;             __builtin_amdgcn_fence(__ATOMIC_RELEASE, "agent");
;             asm volatile("s_waitcnt vmcnt(0)" ::: "memory");
;             const unsigned og = xb_add(&bar[XB_TOP], 1u);
;             const unsigned tg = og / nx;
;             if (og + 1u == (tg + 1u) * nx) xb_add(&bar[XB_TOPGEN], 1u);
;             else XB_SPIN(xb_ld(&bar[XB_TOPGEN]) == tg, bar);
;             __builtin_amdgcn_fence(__ATOMIC_ACQUIRE, "agent");
;             xb_add(&bar[XB_XGEN(b.x)], 1u);
;             asm volatile("s_waitcnt vmcnt(0)" ::: "memory");
;         } else {
;             XB_SPIN(xb_ld(&bar[XB_XGEN(b.x)]) == gen, bar);
;             __builtin_amdgcn_fence(__ATOMIC_ACQUIRE, "agent");
;             asm volatile("s_waitcnt vmcnt(0)" ::: "memory");
;         }
.LBB0_430:
	s_or_b64 exec, exec, s[22:23]
	v_cvt_f32_u32_e32 v5, v3
	s_waitcnt vmcnt(0)
	v_readfirstlane_b32 s22, v4
	v_sub_u32_e32 v4, 0, v3
	v_rcp_iflag_f32_e32 v5, v5
	v_add_u32_e32 v6, s22, v1
	v_mul_f32_e32 v5, 0x4f7ffffe, v5
	v_cvt_u32_f32_e32 v5, v5
	v_mul_lo_u32 v1, v4, v5
	v_mul_hi_u32 v1, v5, v1
	v_add_u32_e32 v1, v5, v1
	v_mul_hi_u32 v1, v6, v1
	v_mul_lo_u32 v4, v1, v3
	v_sub_u32_e32 v4, v6, v4
	v_add_u32_e32 v5, 1, v1
	v_cmp_ge_u32_e32 vcc, v4, v3
	s_nop 1
	v_cndmask_b32_e32 v1, v1, v5, vcc
	v_sub_u32_e32 v5, v4, v3
	v_cndmask_b32_e32 v4, v4, v5, vcc
	v_add_u32_e32 v5, 1, v1
	v_cmp_ge_u32_e32 vcc, v4, v3
	v_add_u32_e32 v4, 1, v6
	s_nop 0
	v_cndmask_b32_e32 v1, v1, v5, vcc
	v_mul_lo_u32 v5, v3, v1
	v_add_u32_e32 v3, v5, v3
	v_cmp_ne_u32_e32 vcc, v4, v3
	s_and_saveexec_b64 s[22:23], vcc
	s_xor_b64 s[22:23], exec, s[22:23]
	s_cbranch_execz .LBB0_444
	v_sub_u32_e32 v2, v6, v5
	v_and_b32_e32 v2, 7, v2
	v_cmp_eq_u32_e32 vcc, 0, v2
	s_cbranch_vccz .Learly_wb_skip_1
	buffer_wbl2 sc1
.Learly_wb_skip_1:
	v_readlane_b32 s4, v254, 3
	v_readlane_b32 s5, v254, 4
	s_waitcnt lgkmcnt(0)
	s_nop 3
	global_load_dword v2, v0, s[4:5] sc1
	s_waitcnt vmcnt(0)
	v_cmp_eq_u32_e32 vcc, v2, v1
	s_and_saveexec_b64 s[24:25], vcc
	s_cbranch_execz .LBB0_443
	s_mov_b32 s36, 1
	s_mov_b64 s[30:31], 0
	s_branch .LBB0_434

; __device__ __forceinline__ unsigned xb_ld(unsigned* p)              { return __hip_atomic_load(p, __ATOMIC_RELAXED, __HIP_MEMORY_SCOPE_AGENT); }
; __device__ __forceinline__ unsigned xb_add(unsigned* p, unsigned v) { return __hip_atomic_fetch_add(p, v, __ATOMIC_RELAXED, __HIP_MEMORY_SCOPE_AGENT); }
; #define XB_SPIN(cond, bar) do { unsigned _sp = 0; while (cond) { __builtin_amdgcn_s_sleep(1); \
;     if ((++_sp & 255u) == 0u) { if (xb_ld(&(bar)[XB_TMO])) break; if (_sp > XB_SPIN_CAP) { atomicAdd(&(bar)[XB_TMO], 1u); break; } } } } while (0)
; __device__ __forceinline__ void xcd_barrier(const XcdBarrier& b) {
;     ...
;         const unsigned old = xb_add(&bar[XB_XSUB(b.x)], 1u);
;         const unsigned gen = old / nloc;
;         if (old + 1u == (gen + 1u) * nloc) {
;             __builtin_amdgcn_fence(__ATOMIC_RELEASE, "agent");
;             asm volatile("s_waitcnt vmcnt(0)" ::: "memory");
;             const unsigned og = xb_add(&bar[XB_TOP], 1u);
;             const unsigned tg = og / nx;
;             if (og + 1u == (tg + 1u) * nx) xb_add(&bar[XB_TOPGEN], 1u);
;             else XB_SPIN(xb_ld(&bar[XB_TOPGEN]) == tg, bar);
;             __builtin_amdgcn_fence(__ATOMIC_ACQUIRE, "agent");
;             xb_add(&bar[XB_XGEN(b.x)], 1u);
;             asm volatile("s_waitcnt vmcnt(0)" ::: "memory");
;         } else {
;             XB_SPIN(xb_ld(&bar[XB_XGEN(b.x)]) == gen, bar);
.LBB0_596:
	s_or_b64 exec, exec, s[18:19]
	v_cvt_f32_u32_e32 v5, v3
	s_waitcnt vmcnt(0)
	v_readfirstlane_b32 s18, v4
	v_sub_u32_e32 v4, 0, v3
	v_rcp_iflag_f32_e32 v5, v5
	v_add_u32_e32 v6, s18, v1
	v_mul_f32_e32 v5, 0x4f7ffffe, v5
	v_cvt_u32_f32_e32 v5, v5
	v_mul_lo_u32 v1, v4, v5
	v_mul_hi_u32 v1, v5, v1
	v_add_u32_e32 v1, v5, v1
	v_mul_hi_u32 v1, v6, v1
	v_mul_lo_u32 v4, v1, v3
	v_sub_u32_e32 v4, v6, v4
	v_add_u32_e32 v5, 1, v1
	v_cmp_ge_u32_e32 vcc, v4, v3
	s_nop 1
	v_cndmask_b32_e32 v1, v1, v5, vcc
	v_sub_u32_e32 v5, v4, v3
	v_cndmask_b32_e32 v4, v4, v5, vcc
	v_add_u32_e32 v5, 1, v1
	v_cmp_ge_u32_e32 vcc, v4, v3
	v_add_u32_e32 v4, 1, v6
	s_nop 0
	v_cndmask_b32_e32 v1, v1, v5, vcc
	v_mul_lo_u32 v5, v3, v1
	v_add_u32_e32 v3, v5, v3
	v_cmp_ne_u32_e32 vcc, v4, v3
	s_and_saveexec_b64 s[18:19], vcc
	s_xor_b64 s[18:19], exec, s[18:19]
	s_cbranch_execz .LBB0_610
	v_sub_u32_e32 v2, v6, v5
	v_and_b32_e32 v2, 7, v2
	v_cmp_eq_u32_e32 vcc, 0, v2
	s_cbranch_vccz .Learly_wb_skip_2
	buffer_wbl2 sc1
.Learly_wb_skip_2:
	v_readlane_b32 s22, v254, 3
	v_readlane_b32 s23, v254, 4
	s_waitcnt lgkmcnt(0)
	s_nop 3
	global_load_dword v2, v0, s[22:23] sc1
	s_waitcnt vmcnt(0)
	v_cmp_eq_u32_e32 vcc, v2, v1
	s_and_saveexec_b64 s[22:23], vcc
	s_cbranch_execz .LBB0_609
	s_mov_b32 s36, 1
	s_mov_b64 s[24:25], 0
	s_branch .LBB0_600

; __device__ __forceinline__ unsigned xb_ld(unsigned* p)              { return __hip_atomic_load(p, __ATOMIC_RELAXED, __HIP_MEMORY_SCOPE_AGENT); }
; #define XB_SPIN(cond, bar) do { unsigned _sp = 0; while (cond) { __builtin_amdgcn_s_sleep(1); \
;     if ((++_sp & 255u) == 0u) { if (xb_ld(&(bar)[XB_TMO])) break; if (_sp > XB_SPIN_CAP) { atomicAdd(&(bar)[XB_TMO], 1u); break; } } } } while (0)
; __device__ __forceinline__ void xcd_barrier(const XcdBarrier& b) {
;     ...
;         } else {
;             XB_SPIN(xb_ld(&bar[XB_XGEN(b.x)]) == gen, bar);
;             __builtin_amdgcn_fence(__ATOMIC_ACQUIRE, "agent");
;             asm volatile("s_waitcnt vmcnt(0)" ::: "memory");
.Learly_wb_skip_3:
	v_readlane_b32 s4, v254, 3
	v_readlane_b32 s5, v254, 4
	s_waitcnt lgkmcnt(0)
	s_nop 3
	global_load_dword v2, v0, s[4:5] sc1
	s_waitcnt vmcnt(0)
	v_cmp_eq_u32_e32 vcc, v2, v1
	s_and_saveexec_b64 s[22:23], vcc
	s_cbranch_execz .LBB0_687
	s_mov_b32 s36, 1
	s_mov_b64 s[24:25], 0
	s_branch .LBB0_678

; __device__ __forceinline__ unsigned xb_ld(unsigned* p)              { return __hip_atomic_load(p, __ATOMIC_RELAXED, __HIP_MEMORY_SCOPE_AGENT); }
; __device__ __forceinline__ unsigned xb_add(unsigned* p, unsigned v) { return __hip_atomic_fetch_add(p, v, __ATOMIC_RELAXED, __HIP_MEMORY_SCOPE_AGENT); }
; #define XB_SPIN(cond, bar) do { unsigned _sp = 0; while (cond) { __builtin_amdgcn_s_sleep(1); \
;     if ((++_sp & 255u) == 0u) { if (xb_ld(&(bar)[XB_TMO])) break; if (_sp > XB_SPIN_CAP) { atomicAdd(&(bar)[XB_TMO], 1u); break; } } } } while (0)
; __device__ __forceinline__ void xcd_barrier(const XcdBarrier& b) {
;     ...
;         const unsigned old = xb_add(&bar[XB_XSUB(b.x)], 1u);
;         const unsigned gen = old / nloc;
;         if (old + 1u == (gen + 1u) * nloc) {
;             __builtin_amdgcn_fence(__ATOMIC_RELEASE, "agent");
;             asm volatile("s_waitcnt vmcnt(0)" ::: "memory");
;             const unsigned og = xb_add(&bar[XB_TOP], 1u);
;             const unsigned tg = og / nx;
;             if (og + 1u == (tg + 1u) * nx) xb_add(&bar[XB_TOPGEN], 1u);
;             else XB_SPIN(xb_ld(&bar[XB_TOPGEN]) == tg, bar);
;             __builtin_amdgcn_fence(__ATOMIC_ACQUIRE, "agent");
;             xb_add(&bar[XB_XGEN(b.x)], 1u);
;             asm volatile("s_waitcnt vmcnt(0)" ::: "memory");
;         } else {
;             XB_SPIN(xb_ld(&bar[XB_XGEN(b.x)]) == gen, bar);
.LBB0_772:
	s_or_b64 exec, exec, s[18:19]
	v_cvt_f32_u32_e32 v5, v3
	s_waitcnt vmcnt(0)
	v_readfirstlane_b32 s4, v4
	v_sub_u32_e32 v4, 0, v3
	v_rcp_iflag_f32_e32 v5, v5
	v_add_u32_e32 v6, s4, v1
	v_mul_f32_e32 v5, 0x4f7ffffe, v5
	v_cvt_u32_f32_e32 v5, v5
	v_mul_lo_u32 v1, v4, v5
	v_mul_hi_u32 v1, v5, v1
	v_add_u32_e32 v1, v5, v1
	v_mul_hi_u32 v1, v6, v1
	v_mul_lo_u32 v4, v1, v3
	v_sub_u32_e32 v4, v6, v4
	v_add_u32_e32 v5, 1, v1
	v_cmp_ge_u32_e32 vcc, v4, v3
	s_nop 1
	v_cndmask_b32_e32 v1, v1, v5, vcc
	v_sub_u32_e32 v5, v4, v3
	v_cndmask_b32_e32 v4, v4, v5, vcc
	v_add_u32_e32 v5, 1, v1
	v_cmp_ge_u32_e32 vcc, v4, v3
	v_add_u32_e32 v4, 1, v6
	s_nop 0
	v_cndmask_b32_e32 v1, v1, v5, vcc
	v_mul_lo_u32 v5, v3, v1
	v_add_u32_e32 v3, v5, v3
	v_cmp_ne_u32_e32 vcc, v4, v3
	s_and_saveexec_b64 s[18:19], vcc
	s_xor_b64 s[18:19], exec, s[18:19]
	s_cbranch_execz .LBB0_786
	v_sub_u32_e32 v2, v6, v5
	v_and_b32_e32 v2, 7, v2
	v_cmp_eq_u32_e32 vcc, 0, v2
	s_cbranch_vccz .Learly_wb_skip_4
	buffer_wbl2 sc1

; __device__ __forceinline__ unsigned xb_ld(unsigned* p)              { return __hip_atomic_load(p, __ATOMIC_RELAXED, __HIP_MEMORY_SCOPE_AGENT); }
; #define XB_SPIN(cond, bar) do { unsigned _sp = 0; while (cond) { __builtin_amdgcn_s_sleep(1); \
;     if ((++_sp & 255u) == 0u) { if (xb_ld(&(bar)[XB_TMO])) break; if (_sp > XB_SPIN_CAP) { atomicAdd(&(bar)[XB_TMO], 1u); break; } } } } while (0)
; __device__ __forceinline__ void xcd_barrier(const XcdBarrier& b) {
;     ...
;         } else {
;             XB_SPIN(xb_ld(&bar[XB_XGEN(b.x)]) == gen, bar);
;             __builtin_amdgcn_fence(__ATOMIC_ACQUIRE, "agent");
;             asm volatile("s_waitcnt vmcnt(0)" ::: "memory");
.Learly_wb_skip_7:
	v_readlane_b32 s4, v254, 3
	v_readlane_b32 s5, v254, 4
	s_waitcnt lgkmcnt(0)
	s_nop 3
	global_load_dword v2, v0, s[4:5] sc1
	s_waitcnt vmcnt(0)
	v_cmp_eq_u32_e32 vcc, v2, v1
	s_and_saveexec_b64 s[20:21], vcc
	s_cbranch_execz .LBB0_1057
	s_mov_b32 s36, 1
	s_mov_b64 s[22:23], 0
	s_branch .LBB0_1048
